# P7 row order remapped: sweep k writes, for every XCD, the h2 rows that P8 (reversed order) consumes k-th, so the A operand is read before the F writes evict it
# speedup vs baseline: 1.0122x; 1.0069x over previous
.LBB0_828:
	s_cmp_lt_i32 s82, 8
	s_cselect_b64 s[4:5], -1, 0
	s_and_b64 s[4:5], s[4:5], s[0:1]
	s_and_b64 s[0:1], s[4:5], s[84:85]
	s_andn2_b64 vcc, exec, s[0:1]
	s_cbranch_vccnz .LBB0_835
	v_mov_b32_e32 v5, 0
	v_readlane_b32 s8, v254, 0
	s_ashr_i32 s81, s80, 31
	s_lshr_b32 s40, s80, 9
	s_mulk_i32 s40, 0x1400
	s_and_b32 s41, s80, 0x1ff
	s_add_i32 s43, s40, s41
	s_add_i32 s40, s43, 0x1200
	s_mov_b32 s41, 0
	v_mov_b32_e32 v213, v5
	v_readlane_b32 s9, v254, 1
	s_movk_i32 s6, 0xfe00
	s_lshl_b64 s[0:1], s[40:41], 11
	v_lshl_add_u64 v[6:7], s[8:9], 0, v[212:213]
	s_add_u32 s8, s78, s0
	s_addc_u32 s9, s79, s1
	s_add_i32 s16, s40, 0x5000
	v_readlane_b32 s10, v254, 2
	v_readlane_b32 s11, v254, 3
	v_readlane_b32 s12, v254, 4
	v_readlane_b32 s13, v254, 5
	v_readlane_b32 s14, v254, 6
	v_readlane_b32 s15, v254, 7
	s_ashr_i32 s7, s6, 31
	s_ashr_i32 s17, s16, 31
	s_lshl_b64 s[10:11], s[6:7], 11
	s_lshl_b64 s[12:13], s[40:41], 10
	s_lshl_b64 s[14:15], s[6:7], 10
	s_lshl_b64 s[20:21], s[16:17], 11
	s_add_u32 s16, s76, s20
	s_addc_u32 s17, s77, s21
	s_add_u32 s18, s76, s0
	v_or_b32_e32 v8, 0x300, v216
	s_addc_u32 s19, s77, s1
	v_mbcnt_hi_u32_b32 v47, -1, v211
	v_or_b32_e32 v0, 0x100, v216
	v_or_b32_e32 v2, 0x200, v216
	v_lshlrev_b32_e32 v4, 1, v8
	s_add_u32 s20, s78, s20
	v_and_b32_e32 v1, 64, v47
	s_waitcnt lgkmcnt(0)
	v_lshl_add_u64 v[10:11], s[22:23], 0, v[4:5]
	v_mov_b32_e32 v215, v5
	s_addc_u32 s21, s79, s21
	v_mov_b32_e32 v9, 0x358637bd
	s_mov_b32 s3, 0xf800000
	v_mov_b32_e32 v46, 0x260
	s_brev_b32 s7, 64
	v_add_u32_e32 v48, 64, v1
	v_xor_b32_e32 v49, 1, v47
	v_xor_b32_e32 v50, 2, v47
	v_xor_b32_e32 v51, 4, v47
	v_xor_b32_e32 v52, 8, v47
	v_xor_b32_e32 v53, 16, v47
	v_xor_b32_e32 v54, 32, v47
	v_lshlrev_b32_e32 v55, 2, v216
	v_lshlrev_b32_e32 v56, 2, v0
	v_lshlrev_b32_e32 v57, 2, v2
	s_mov_b32 s35, s40
	s_branch .LBB0_831
.LBB0_830:
	v_lshl_add_u64 v[12:13], s[24:25], 0, v[4:5]
	v_add_co_u32_e32 v20, vcc, 0x3000, v12
	s_add_i32 s35, s35, s6
	s_nop 0
	v_addc_co_u32_e32 v21, vcc, 0, v13, vcc
	v_add_co_u32_e32 v22, vcc, 0x4000, v12
	s_add_u32 s8, s8, s10
	s_nop 0
	v_addc_co_u32_e32 v23, vcc, 0, v13, vcc
	global_load_dwordx4 v[12:15], v[22:23], off
	global_load_dwordx4 v[16:19], v[20:21], off
	s_addc_u32 s9, s9, s11
	s_add_u32 s12, s12, s14
	s_addc_u32 s13, s13, s15
	s_add_u32 s16, s16, s10
	s_addc_u32 s17, s17, s11
	s_add_u32 s18, s18, s10
	s_addc_u32 s19, s19, s11
	s_add_u32 s20, s20, s10
	s_addc_u32 s21, s21, s11
	v_lshl_add_u64 v[20:21], s[26:27], 1, v[10:11]
	s_cmp_ge_i32 s35, s43
	s_waitcnt vmcnt(0)
	v_pk_add_f32 v[14:15], v[14:15], 1.0 op_sel_hi:[1,0]
	v_pk_add_f32 v[12:13], v[12:13], 1.0 op_sel_hi:[1,0]
	v_pk_fma_f32 v[2:3], v[2:3], v[14:15], v[18:19]
	v_pk_fma_f32 v[0:1], v[0:1], v[12:13], v[16:17]
	s_nop 0
	v_cvt_pk_bf16_f32 v0, v0, v1
	v_cvt_pk_bf16_f32 v1, v2, v3
	global_store_dwordx2 v[20:21], v[0:1], off
	s_cbranch_scc0 .LBB0_835
.LBB0_831:
	s_add_i32 s0, s35, 0xffffe000
	s_add_i32 s36, s35, 0x5000
	s_ashr_i32 s0, s0, 12
	s_cmpk_gt_i32 s35, 0x1fff
	s_cselect_b32 s24, s0, 8
	s_mov_b64 s[0:1], -1
	s_cmp_gt_i32 s36, 0x9fff
	s_mul_i32 s28, s24, 0x1800
	v_lshl_add_u64 v[14:15], s[18:19], 0, v[214:215]
	v_lshl_add_u64 v[12:13], s[8:9], 0, v[214:215]
	s_cbranch_scc0 .LBB0_833
	global_load_dwordx2 v[24:25], v[14:15], off
	global_load_dwordx2 v[26:27], v[14:15], off offset:512
	global_load_dwordx2 v[28:29], v[14:15], off offset:1024
	global_load_dwordx2 v[30:31], v[14:15], off offset:1536
	s_ashr_i32 s29, s28, 31
	s_lshl_b64 s[0:1], s[28:29], 2
	s_add_u32 s24, s78, s0
	s_addc_u32 s25, s79, s1
	s_add_u32 s26, s24, 0x3000
	s_addc_u32 s27, s25, 0
	s_add_u32 s30, s24, 0x4000
	global_load_dwordx4 v[0:3], v[6:7], off
	s_addc_u32 s31, s25, 0
	global_load_dwordx4 v[16:19], v55, s[30:31]
	global_load_dwordx4 v[20:23], v55, s[26:27]
	v_cmp_lt_i32_e32 vcc, v49, v48
	s_waitcnt vmcnt(0)
	v_lshlrev_b32_e32 v32, 16, v24
	v_cndmask_b32_e32 v4, v47, v49, vcc
	v_and_b32_e32 v33, 0xffff0000, v24
	v_lshlrev_b32_e32 v24, 16, v25
	v_and_b32_e32 v25, 0xffff0000, v25
	v_lshlrev_b32_e32 v66, 2, v4
	v_lshlrev_b32_e32 v35, 16, v27
	v_lshlrev_b32_e32 v34, 16, v26
	v_and_b32_e32 v27, 0xffff0000, v27
	v_and_b32_e32 v26, 0xffff0000, v26
	v_lshlrev_b32_e32 v36, 16, v28
	v_and_b32_e32 v37, 0xffff0000, v28
	v_lshlrev_b32_e32 v28, 16, v29
	v_and_b32_e32 v29, 0xffff0000, v29
	v_lshlrev_b32_e32 v39, 16, v30
	v_mul_f32_e32 v4, v25, v25
	v_mul_f32_e32 v38, v33, v33
	v_pk_mul_f32 v[42:43], v[26:27], v[26:27]
	v_mov_b32_e32 v45, v39
	v_mul_f32_e32 v44, v29, v29
	v_pk_fma_f32 v[58:59], v[24:25], v[24:25], v[4:5] op_sel_hi:[1,1,0]
	v_pk_fma_f32 v[60:61], v[32:33], v[32:33], v[38:39] op_sel_hi:[1,1,0]
	v_and_b32_e32 v41, 0xffff0000, v30
	v_lshlrev_b32_e32 v30, 16, v31
	v_and_b32_e32 v31, 0xffff0000, v31
	v_mul_f32_e32 v40, v37, v37
	v_pk_fma_f32 v[42:43], v[34:35], v[34:35], v[42:43]
	v_pk_fma_f32 v[64:65], v[28:29], v[28:29], v[44:45] op_sel_hi:[1,1,0]
	v_mov_b32_e32 v38, v60
	v_mov_b32_e32 v44, v58
	v_mul_f32_e32 v67, v41, v41
	v_mul_f32_e32 v68, v30, v30
	v_mul_f32_e32 v69, v31, v31
	v_pk_fma_f32 v[62:63], v[36:37], v[36:37], v[40:41] op_sel_hi:[1,1,0]
	v_pk_add_f32 v[58:59], v[60:61], v[58:59]
	v_pk_add_f32 v[42:43], v[42:43], v[42:43] op_sel:[0,1] op_sel_hi:[1,0]
	v_pk_mul_f32 v[44:45], v[38:39], v[44:45]
	v_mov_b32_e32 v63, v68
	v_mov_b32_e32 v65, v69
	v_mov_b32_e32 v43, v67
	v_mov_b32_e32 v59, v45
	v_pk_add_f32 v[60:61], v[62:63], v[64:65]
	v_pk_add_f32 v[42:43], v[58:59], v[42:43]
	v_cmp_lt_i32_e32 vcc, v50, v48
	v_pk_add_f32 v[42:43], v[42:43], v[60:61]
	v_pk_add_f32 v[18:19], v[18:19], 1.0 op_sel_hi:[1,0]
	v_add_f32_e32 v4, v42, v43
	ds_bpermute_b32 v38, v66, v4
	v_cndmask_b32_e32 v40, v47, v50, vcc
	v_lshlrev_b32_e32 v40, 2, v40
	v_cmp_lt_i32_e32 vcc, v51, v48
	v_add_co_u32_e64 v42, s[0:1], s7, v12
	s_waitcnt lgkmcnt(0)
	v_add_f32_e32 v4, v4, v38
	ds_bpermute_b32 v38, v40, v4
	v_cndmask_b32_e32 v40, v47, v51, vcc
	v_lshlrev_b32_e32 v40, 2, v40
	v_cmp_lt_i32_e32 vcc, v52, v48
	v_addc_co_u32_e64 v43, s[0:1], 0, v13, s[0:1]
	s_waitcnt lgkmcnt(0)
	v_add_f32_e32 v4, v4, v38
	ds_bpermute_b32 v38, v40, v4
	v_cndmask_b32_e32 v40, v47, v52, vcc
	v_lshlrev_b32_e32 v40, 2, v40
	v_cmp_lt_i32_e32 vcc, v53, v48
	v_pk_add_f32 v[16:17], v[16:17], 1.0 op_sel_hi:[1,0]
	s_waitcnt lgkmcnt(0)
	v_add_f32_e32 v4, v4, v38
	ds_bpermute_b32 v38, v40, v4
	v_cndmask_b32_e32 v40, v47, v53, vcc
	v_lshlrev_b32_e32 v40, 2, v40
	v_cmp_lt_i32_e32 vcc, v54, v48
	s_waitcnt lgkmcnt(0)
	v_add_f32_e32 v4, v4, v38
	ds_bpermute_b32 v38, v40, v4
	v_cndmask_b32_e32 v40, v47, v54, vcc
	v_lshlrev_b32_e32 v40, 2, v40
	s_waitcnt lgkmcnt(0)
	v_add_f32_e32 v4, v4, v38
	ds_bpermute_b32 v38, v40, v4
	s_waitcnt lgkmcnt(0)
	v_add_f32_e32 v4, v4, v38
	v_fmamk_f32 v4, v4, 0x3a800000, v9
	v_mul_f32_e32 v38, 0x4f800000, v4
	v_cmp_gt_f32_e32 vcc, s3, v4
	s_nop 1
	v_cndmask_b32_e32 v4, v4, v38, vcc
	v_sqrt_f32_e32 v38, v4
	s_nop 0
	v_add_u32_e32 v40, -1, v38
	v_add_u32_e32 v44, 1, v38
	v_fma_f32 v45, -v40, v38, v4
	v_fma_f32 v58, -v44, v38, v4
	v_cmp_ge_f32_e64 s[0:1], 0, v45
	s_nop 1
	v_cndmask_b32_e64 v38, v38, v40, s[0:1]
	v_cmp_lt_f32_e64 s[0:1], 0, v58
	s_nop 1
	v_cndmask_b32_e64 v38, v38, v44, s[0:1]
	v_mul_f32_e32 v40, 0x37800000, v38
	v_cndmask_b32_e32 v38, v38, v40, vcc
	v_cmp_class_f32_e32 vcc, v4, v46
	s_nop 1
	v_cndmask_b32_e32 v4, v38, v4, vcc
	v_div_scale_f32 v38, s[0:1], v4, v4, 1.0
	v_rcp_f32_e32 v40, v38
	v_div_scale_f32 v44, vcc, 1.0, v4, 1.0
	s_mov_b64 s[0:1], 0
	v_fma_f32 v45, -v38, v40, 1.0
	v_fmac_f32_e32 v40, v45, v40
	v_mul_f32_e32 v45, v44, v40
	v_fma_f32 v58, -v38, v45, v44
	v_fmac_f32_e32 v45, v58, v40
	v_fma_f32 v38, -v38, v45, v44
	v_div_fmas_f32 v38, v38, v40, v45
	v_div_fixup_f32 v4, v38, v4, 1.0
	v_pk_mul_f32 v[24:25], v[4:5], v[24:25] op_sel_hi:[0,1]
	v_pk_mul_f32 v[32:33], v[4:5], v[32:33] op_sel_hi:[0,1]
	v_pk_mul_f32 v[0:1], v[0:1], v[32:33]
	v_pk_mul_f32 v[2:3], v[2:3], v[24:25]
	v_pk_fma_f32 v[0:1], v[16:17], v[0:1], v[20:21]
	v_pk_fma_f32 v[2:3], v[18:19], v[2:3], v[22:23]
	v_cvt_pk_bf16_f32 v0, v0, v1
	v_cvt_pk_bf16_f32 v1, v2, v3
	global_store_dwordx2 v[42:43], v[0:1], off
	global_load_dwordx4 v[0:3], v[6:7], off offset:1024
	s_nop 0
	global_load_dwordx4 v[16:19], v56, s[30:31]
	global_load_dwordx4 v[20:23], v56, s[26:27]
	v_mov_b32_e32 v24, v35
	v_mov_b32_e32 v25, v27
	v_mov_b32_e32 v35, v26
	v_pk_mul_f32 v[24:25], v[4:5], v[24:25] op_sel_hi:[0,1]
	v_pk_mul_f32 v[26:27], v[4:5], v[34:35] op_sel_hi:[0,1]
	v_mov_b32_e32 v40, v39
	s_waitcnt vmcnt(2)
	v_pk_mul_f32 v[0:1], v[0:1], v[26:27]
	v_pk_mul_f32 v[2:3], v[2:3], v[24:25]
	s_waitcnt vmcnt(1)
	v_pk_add_f32 v[18:19], v[18:19], 1.0 op_sel_hi:[1,0]
	v_pk_add_f32 v[16:17], v[16:17], 1.0 op_sel_hi:[1,0]
	s_waitcnt vmcnt(0)
	v_pk_fma_f32 v[2:3], v[18:19], v[2:3], v[22:23]
	v_pk_fma_f32 v[0:1], v[16:17], v[0:1], v[20:21]
	v_pk_mul_f32 v[24:25], v[4:5], v[28:29] op_sel_hi:[0,1]
	v_cvt_pk_bf16_f32 v0, v0, v1
	v_cvt_pk_bf16_f32 v1, v2, v3
	global_store_dwordx2 v[42:43], v[0:1], off offset:512
	global_load_dwordx4 v[0:3], v[6:7], off offset:2048
	s_nop 0
	global_load_dwordx4 v[16:19], v57, s[30:31]
	global_load_dwordx4 v[20:23], v57, s[26:27]
	v_pk_mul_f32 v[26:27], v[4:5], v[36:37] op_sel_hi:[0,1]
	s_waitcnt vmcnt(2)
	v_pk_mul_f32 v[0:1], v[0:1], v[26:27]
	v_pk_mul_f32 v[2:3], v[2:3], v[24:25]
	s_waitcnt vmcnt(1)
	v_pk_add_f32 v[18:19], v[18:19], 1.0 op_sel_hi:[1,0]
	v_pk_add_f32 v[16:17], v[16:17], 1.0 op_sel_hi:[1,0]
	s_waitcnt vmcnt(0)
	v_pk_fma_f32 v[2:3], v[18:19], v[2:3], v[22:23]
	v_pk_fma_f32 v[0:1], v[16:17], v[0:1], v[20:21]
	v_pk_mul_f32 v[16:17], v[30:31], v[4:5] op_sel_hi:[1,0]
	v_cvt_pk_bf16_f32 v0, v0, v1
	v_cvt_pk_bf16_f32 v1, v2, v3
	global_store_dwordx2 v[42:43], v[0:1], off offset:1024
	global_load_dwordx4 v[0:3], v[6:7], off offset:3072
	v_pk_mul_f32 v[18:19], v[40:41], v[4:5] op_sel_hi:[1,0]
	s_waitcnt vmcnt(0)
	v_pk_mul_f32 v[2:3], v[16:17], v[2:3]
	v_pk_mul_f32 v[0:1], v[18:19], v[0:1]
